# gates epilogue: bias+scale folded into one fma, log2e folded into the per-channel decay constant, (1-a)(1+a) as one fma (256 fewer VALU per wave per unit)
# speedup vs baseline: 1.0025x; 1.0025x over previous
.LBB0_461:
	v_lshl_or_b32 v166, s78, 7, v172
	v_ashrrev_i32_e32 v167, 31, v166
	v_readlane_b32 s4, v254, 4
	v_lshlrev_b64 v[144:145], 2, v[166:167]
	v_readlane_b32 s5, v254, 5
	v_readlane_b32 s6, v254, 6
	v_readlane_b32 s7, v254, 7
	v_readlane_b32 s8, v254, 8
	v_readlane_b32 s9, v254, 9
	v_readlane_b32 s10, v254, 10
	v_readlane_b32 s11, v254, 11
	v_readlane_b32 s12, v254, 12
	v_readlane_b32 s13, v254, 13
	v_readlane_b32 s14, v254, 14
	v_readlane_b32 s15, v254, 15
	v_readlane_b32 s16, v254, 16
	v_readlane_b32 s17, v254, 17
	v_readlane_b32 s18, v254, 18
	v_readlane_b32 s19, v254, 19
	v_lshl_add_u64 v[32:33], s[16:17], 0, v[144:145]
	v_readlane_b32 s4, v254, 21
	v_readlane_b32 s5, v254, 22
	v_readlane_b32 s6, v254, 23
	v_readlane_b32 s7, v254, 24
	v_lshl_add_u64 v[44:45], s[4:5], 0, v[144:145]
	global_load_dwordx4 v[28:31], v[32:33], off offset:16
	global_load_dwordx4 v[40:43], v[32:33], off
	v_lshl_add_u64 v[148:149], s[6:7], 0, v[144:145]
	global_load_dwordx4 v[32:35], v[44:45], off offset:16
	s_nop 0
	global_load_dwordx4 v[44:47], v[44:45], off
	s_nop 0
	global_load_dwordx4 v[144:147], v[148:149], off offset:16
	s_nop 0
	v_and_b32_e32 v244, 31, v152
	v_lshlrev_b32_e32 v244, 2, v244
	v_lshrrev_b32_e32 v245, 4, v152
	v_lshlrev_b32_e32 v245, 5, v245
	v_sub_u32_e32 v244, v244, v245
	v_ashrrev_i32_e32 v245, 31, v244
	v_lshl_add_u64 v[244:245], v[148:149], 0, v[244:245]
	global_load_dword v148, v[244:245], off
	v_lshl_add_u32 v168, s0, 8, v170
	v_readlane_b32 s8, v254, 25
	v_readlane_b32 s9, v254, 26
	s_mov_b64 s[8:9], 0x40000
	v_readlane_b32 s10, v254, 27
	v_readlane_b32 s11, v254, 28
	v_readlane_b32 s12, v254, 29
	v_readlane_b32 s13, v254, 30
	v_readlane_b32 s14, v254, 31
	v_readlane_b32 s15, v254, 32
	v_readlane_b32 s16, v254, 33
	v_readlane_b32 s17, v254, 34
	v_readlane_b32 s18, v254, 35
	v_readlane_b32 s19, v254, 36
	s_waitcnt vmcnt(0)
	v_mul_f32_e32 v28, 0xbfb8aa3b, v28
	v_mul_f32_e32 v29, 0xbfb8aa3b, v29
	v_mul_f32_e32 v30, 0xbfb8aa3b, v30
	v_mul_f32_e32 v31, 0xbfb8aa3b, v31
	v_mul_f32_e32 v32, 0xbfb8aa3b, v32
	v_mul_f32_e32 v33, 0xbfb8aa3b, v33
	v_mul_f32_e32 v34, 0xbfb8aa3b, v34
	v_mul_f32_e32 v35, 0xbfb8aa3b, v35
	v_mul_f32_e32 v40, 0xbfb8aa3b, v40
	v_mul_f32_e32 v41, 0xbfb8aa3b, v41
	v_mul_f32_e32 v42, 0xbfb8aa3b, v42
	v_mul_f32_e32 v43, 0xbfb8aa3b, v43
	v_mul_f32_e32 v44, 0xbfb8aa3b, v44
	v_mul_f32_e32 v45, 0xbfb8aa3b, v45
	v_mul_f32_e32 v46, 0xbfb8aa3b, v46
	v_mul_f32_e32 v47, 0xbfb8aa3b, v47
	v_fmamk_f32 v140, v140, 0xbfb8aa3b, v40
	v_mul_f32_e32 v144, 0xbfb8aa3b, v144
	v_mul_f32_e32 v148, 0xbfb8aa3b, v148
	v_exp_f32_e32 v148, v148
	v_exp_f32_e32 v144, v144
	v_exp_f32_e32 v140, v140
	v_add_f32_e32 v169, 1.0, v148
	v_add_f32_e32 v187, -1.0, v169
	v_sub_f32_e32 v188, v187, v169
	v_add_f32_e32 v188, 1.0, v188
	v_sub_f32_e32 v187, v148, v187
	v_add_f32_e32 v187, v187, v188
	v_frexp_mant_f32_e32 v188, v169
	v_cmp_gt_f32_e32 vcc, s93, v188
	v_cvt_f64_f32_e32 v[188:189], v169
	v_frexp_exp_i32_f64_e32 v188, v[188:189]
	v_subbrev_co_u32_e32 v188, vcc, 0, v188, vcc
	v_sub_u32_e32 v189, 0, v188
	v_ldexp_f32 v169, v169, v189
	v_ldexp_f32 v187, v187, v189
	v_add_f32_e32 v189, -1.0, v169
	v_add_f32_e32 v190, 1.0, v189
	v_sub_f32_e32 v190, v169, v190
	v_add_f32_e32 v190, v187, v190
	v_add_f32_e32 v191, v189, v190
	v_sub_f32_e32 v189, v191, v189
	v_sub_f32_e32 v189, v190, v189
	v_add_f32_e32 v190, 1.0, v169
	v_add_f32_e32 v192, -1.0, v190
	v_sub_f32_e32 v169, v169, v192
	v_add_f32_e32 v169, v187, v169
	v_add_f32_e32 v187, v190, v169
	v_sub_f32_e32 v190, v187, v190
	v_sub_f32_e32 v169, v169, v190
	v_rcp_f32_e32 v190, v187
	v_cvt_f32_i32_e32 v188, v188
	v_cmp_neq_f32_e32 vcc, s95, v148
	v_add_f32_e32 v140, 1.0, v140
	v_mul_f32_e32 v192, v191, v190
	v_mul_f32_e32 v193, v187, v192
	v_fma_f32 v194, v192, v187, -v193
	v_fmac_f32_e32 v194, v192, v169
	v_add_f32_e32 v195, v193, v194
	v_sub_f32_e32 v196, v191, v195
	v_sub_f32_e32 v191, v191, v196
	v_sub_f32_e32 v193, v195, v193
	v_sub_f32_e32 v191, v191, v195
	v_add_f32_e32 v189, v189, v191
	v_sub_f32_e32 v191, v193, v194
	v_add_f32_e32 v189, v191, v189
	v_add_f32_e32 v191, v196, v189
	v_mul_f32_e32 v193, v190, v191
	v_mul_f32_e32 v194, v187, v193
	v_fma_f32 v187, v193, v187, -v194
	v_fmac_f32_e32 v187, v193, v169
	v_sub_f32_e32 v169, v196, v191
	v_add_f32_e32 v169, v189, v169
	v_add_f32_e32 v189, v194, v187
	v_sub_f32_e32 v195, v191, v189
	v_sub_f32_e32 v191, v191, v195
	v_sub_f32_e32 v194, v189, v194
	v_sub_f32_e32 v189, v191, v189
	v_add_f32_e32 v169, v169, v189
	v_sub_f32_e32 v187, v194, v187
	v_add_f32_e32 v169, v187, v169
	v_add_f32_e32 v187, v192, v193
	v_add_f32_e32 v169, v195, v169
	v_sub_f32_e32 v189, v187, v192
	v_mul_f32_e32 v169, v190, v169
	v_sub_f32_e32 v189, v193, v189
	v_add_f32_e32 v169, v189, v169
	v_mul_f32_e32 v192, 0x3f317218, v188
	v_add_f32_e32 v189, v187, v169
	v_fma_f32 v193, v188, s94, -v192
	v_mul_f32_e32 v190, v189, v189
	v_fmac_f32_e32 v193, 0xb102e308, v188
	v_sub_f32_e32 v187, v189, v187
	v_fmamk_f32 v191, v190, 0x3e9b6dac, v183
	v_sub_f32_e32 v169, v169, v187
	v_add_f32_e32 v187, v192, v193
	v_fmaak_f32 v191, v190, v191, 0x3f2aaada
	v_sub_f32_e32 v188, v187, v192
	v_ldexp_f32 v192, v189, 1
	v_mul_f32_e32 v189, v189, v190
	v_mul_f32_e32 v189, v189, v191
	v_add_f32_e32 v190, v192, v189
	v_sub_f32_e32 v191, v190, v192
	v_ldexp_f32 v169, v169, 1
	v_sub_f32_e32 v189, v189, v191
	v_add_f32_e32 v169, v169, v189
	v_add_f32_e32 v189, v190, v169
	v_sub_f32_e32 v190, v189, v190
	v_sub_f32_e32 v169, v169, v190
	v_add_f32_e32 v190, v187, v189
	v_sub_f32_e32 v191, v190, v187
	v_sub_f32_e32 v192, v190, v191
	v_sub_f32_e32 v188, v193, v188
	v_sub_f32_e32 v187, v187, v192
	v_sub_f32_e32 v189, v189, v191
	v_add_f32_e32 v187, v189, v187
	v_add_f32_e32 v189, v188, v169
	v_sub_f32_e32 v191, v189, v188
	v_sub_f32_e32 v192, v189, v191
	v_sub_f32_e32 v188, v188, v192
	v_sub_f32_e32 v169, v169, v191
	v_add_f32_e32 v187, v189, v187
	v_add_f32_e32 v169, v169, v188
	v_add_f32_e32 v188, v190, v187
	v_sub_f32_e32 v189, v188, v190
	v_sub_f32_e32 v187, v187, v189
	v_add_f32_e32 v169, v169, v187
	v_add_f32_e32 v169, v188, v169
	v_cndmask_b32_e32 v169, v184, v169, vcc
	v_cmp_ngt_f32_e32 vcc, -1.0, v148
	v_rcp_f32_e32 v140, v140
	v_fmamk_f32 v136, v136, 0xbfb8aa3b, v44
	v_cndmask_b32_e32 v169, v185, v169, vcc
	v_cmp_neq_f32_e32 vcc, -1.0, v148
	v_exp_f32_e32 v136, v136
	v_cndmask_b32_e32 v169, v186, v169, vcc
	v_cmp_lt_f32_e64 vcc, |v148|, s96
	v_add_f32_e32 v136, 1.0, v136
	v_rcp_f32_e32 v136, v136
	v_cndmask_b32_e32 v148, v169, v148, vcc
	v_add_f32_e32 v169, 1.0, v144
	v_mul_f32_e32 v187, 0xc1000000, v148
	v_lshrrev_b32_e32 v244, 4, v152
	v_lshlrev_b32_e32 v244, 5, v244
	ds_bpermute_b32 v236, v244, v187
	v_add_u32_e32 v245, 4, v244
	ds_bpermute_b32 v237, v245, v187
	v_add_u32_e32 v245, 8, v244
	ds_bpermute_b32 v238, v245, v187
	v_add_u32_e32 v245, 12, v244
	ds_bpermute_b32 v239, v245, v187
	v_add_u32_e32 v245, 16, v244
	ds_bpermute_b32 v240, v245, v187
	v_add_u32_e32 v245, 20, v244
	ds_bpermute_b32 v241, v245, v187
	v_add_u32_e32 v245, 24, v244
	ds_bpermute_b32 v242, v245, v187
	v_add_u32_e32 v245, 28, v244
	ds_bpermute_b32 v243, v245, v187
	s_waitcnt lgkmcnt(0)
	v_mul_f32_e32 v236, 0x3fb8aa3b, v236
	v_mul_f32_e32 v237, 0x3fb8aa3b, v237
	v_mul_f32_e32 v238, 0x3fb8aa3b, v238
	v_mul_f32_e32 v239, 0x3fb8aa3b, v239
	v_mul_f32_e32 v240, 0x3fb8aa3b, v240
	v_mul_f32_e32 v241, 0x3fb8aa3b, v241
	v_mul_f32_e32 v242, 0x3fb8aa3b, v242
	v_mul_f32_e32 v243, 0x3fb8aa3b, v243
	v_mov_b32_e32 v187, v236
	v_mul_f32_e32 v140, v140, v187
	v_exp_f32_e32 v140, v140
	v_fmamk_f32 v137, v137, 0xbfb8aa3b, v45
	v_exp_f32_e32 v137, v137
	s_nop 0
	v_add_f32_e32 v137, 1.0, v137
	v_rcp_f32_e32 v137, v137
	v_mov_b32_e32 v188, v240
	v_fmamk_f32 v138, v138, 0xbfb8aa3b, v46
	v_exp_f32_e32 v138, v138
	v_fmamk_f32 v132, v132, 0xbfb8aa3b, v28
	v_add_f32_e32 v138, 1.0, v138
	v_rcp_f32_e32 v138, v138
	v_exp_f32_e32 v132, v132
	s_nop 0
	v_add_f32_e32 v132, 1.0, v132
	v_fmamk_f32 v139, v139, 0xbfb8aa3b, v47
	v_rcp_f32_e32 v132, v132
	v_mov_b32_e32 v190, v237
	v_exp_f32_e32 v139, v139
	v_mul_f32_e32 v132, v132, v188
	v_add_f32_e32 v139, 1.0, v139
	v_rcp_f32_e32 v139, v139
	v_exp_f32_e32 v132, v132
	v_fmamk_f32 v128, v128, 0xbfb8aa3b, v32
	v_exp_f32_e32 v128, v128
	v_mov_b32_e32 v189, v241
	v_add_f32_e32 v128, 1.0, v128
	v_rcp_f32_e32 v128, v128
	v_fmamk_f32 v129, v129, 0xbfb8aa3b, v33
	v_exp_f32_e32 v129, v129
	s_nop 0
	v_add_f32_e32 v129, 1.0, v129
	v_rcp_f32_e32 v129, v129
	v_fmamk_f32 v124, v124, 0xbfb8aa3b, v40
	v_exp_f32_e32 v124, v124
	v_mov_b32_e32 v191, v238
	v_add_f32_e32 v124, 1.0, v124
	v_rcp_f32_e32 v124, v124
	v_fmamk_f32 v120, v120, 0xbfb8aa3b, v44
	v_mul_f32_e32 v124, v124, v187
	v_exp_f32_e32 v124, v124
	v_exp_f32_e32 v120, v120
	s_nop 0
	v_add_f32_e32 v120, 1.0, v120
	v_rcp_f32_e32 v120, v120
	v_mov_b32_e32 v150, v242
	v_fmamk_f32 v121, v121, 0xbfb8aa3b, v45
	v_exp_f32_e32 v121, v121
	s_nop 0
	v_add_f32_e32 v121, 1.0, v121
	v_rcp_f32_e32 v121, v121
	v_fmamk_f32 v122, v122, 0xbfb8aa3b, v46
	v_exp_f32_e32 v122, v122
	s_nop 0
	v_add_f32_e32 v122, 1.0, v122
	v_rcp_f32_e32 v122, v122
	v_mov_b32_e32 v192, v239
	v_mul_f32_e32 v144, 0xbfb8aa3b, v147
	v_exp_f32_e32 v146, v144
	v_fmamk_f32 v116, v116, 0xbfb8aa3b, v28
	v_exp_f32_e32 v116, v116
	s_nop 0
	v_add_f32_e32 v116, 1.0, v116
	v_ashrrev_i32_e32 v169, 31, v168
	v_fmamk_f32 v123, v123, 0xbfb8aa3b, v47
	v_rcp_f32_e32 v116, v116
	v_exp_f32_e32 v123, v123
	v_cmp_lt_f32_e64 vcc, |v146|, s96
	v_mul_f32_e32 v116, v116, v188
	v_add_f32_e32 v123, 1.0, v123
	v_mov_b32_e32 v151, v243
	v_lshlrev_b64 v[144:145], 10, v[168:169]
	v_lshl_add_u64 v[144:145], v[144:145], 0, v[166:167]
	v_lshlrev_b64 v[148:149], 1, v[144:145]
	v_lshl_add_u64 v[144:145], s[30:31], 0, v[148:149]
	global_load_dwordx4 v[144:147], v[144:145], off
	v_rcp_f32_e32 v123, v123
	v_exp_f32_e32 v116, v116
	v_fmamk_f32 v112, v112, 0xbfb8aa3b, v32
	v_exp_f32_e32 v112, v112
	v_fmamk_f32 v113, v113, 0xbfb8aa3b, v33
	v_exp_f32_e32 v113, v113
	v_add_f32_e32 v112, 1.0, v112
	v_rcp_f32_e32 v112, v112
	v_add_f32_e32 v113, 1.0, v113
	v_rcp_f32_e32 v113, v113
	v_fmamk_f32 v108, v108, 0xbfb8aa3b, v40
	v_exp_f32_e32 v108, v108
	v_fmamk_f32 v104, v104, 0xbfb8aa3b, v44
	v_exp_f32_e32 v104, v104
	v_add_f32_e32 v108, 1.0, v108
	v_rcp_f32_e32 v108, v108
	v_add_f32_e32 v104, 1.0, v104
	v_rcp_f32_e32 v104, v104
	v_mul_f32_e32 v108, v108, v187
	v_exp_f32_e32 v108, v108
	v_fmamk_f32 v105, v105, 0xbfb8aa3b, v45
	v_exp_f32_e32 v105, v105
	v_fmamk_f32 v106, v106, 0xbfb8aa3b, v46
	v_exp_f32_e32 v106, v106
	v_add_f32_e32 v105, 1.0, v105
	v_rcp_f32_e32 v105, v105
	v_add_f32_e32 v106, 1.0, v106
	v_rcp_f32_e32 v106, v106
	v_fmamk_f32 v100, v100, 0xbfb8aa3b, v28
	v_exp_f32_e32 v100, v100
	v_fmamk_f32 v107, v107, 0xbfb8aa3b, v47
	v_exp_f32_e32 v107, v107
	v_add_f32_e32 v100, 1.0, v100
	v_rcp_f32_e32 v100, v100
	v_add_f32_e32 v107, 1.0, v107
	v_rcp_f32_e32 v107, v107
	v_mul_f32_e32 v100, v100, v188
	v_exp_f32_e32 v100, v100
	v_fmamk_f32 v96, v96, 0xbfb8aa3b, v32
	v_exp_f32_e32 v96, v96
	v_fmamk_f32 v97, v97, 0xbfb8aa3b, v33
	v_exp_f32_e32 v97, v97
	v_add_f32_e32 v96, 1.0, v96
	v_rcp_f32_e32 v96, v96
	v_add_f32_e32 v97, 1.0, v97
	v_rcp_f32_e32 v97, v97
	v_fmamk_f32 v92, v92, 0xbfb8aa3b, v40
	v_exp_f32_e32 v92, v92
	v_fmamk_f32 v88, v88, 0xbfb8aa3b, v44
	v_exp_f32_e32 v88, v88
	v_add_f32_e32 v92, 1.0, v92
	v_rcp_f32_e32 v92, v92
	v_add_f32_e32 v88, 1.0, v88
	v_rcp_f32_e32 v88, v88
	v_mul_f32_e32 v92, v92, v187
	v_exp_f32_e32 v92, v92
	v_fmamk_f32 v89, v89, 0xbfb8aa3b, v45
	v_exp_f32_e32 v89, v89
	v_fmamk_f32 v90, v90, 0xbfb8aa3b, v46
	v_exp_f32_e32 v90, v90
	v_add_f32_e32 v89, 1.0, v89
	s_waitcnt vmcnt(0)
	v_lshlrev_b32_e32 v169, 16, v144
	v_and_b32_e32 v193, 0xffff0000, v144
	v_lshlrev_b32_e32 v196, 16, v147
	v_and_b32_e32 v144, 0xffff0000, v147
	v_sub_f32_e32 v147, 1.0, v140
	v_fma_f32 v140, -v140, v140, 1.0
	v_max_f32_e32 v140, 0, v140
	v_sqrt_f32_e32 v140, v140
	v_lshlrev_b32_e32 v194, 16, v145
	v_and_b32_e32 v145, 0xffff0000, v145
	v_lshlrev_b32_e32 v195, 16, v146
	v_mul_f32_e32 v136, v136, v140
	v_fmamk_f32 v140, v141, 0xbfb8aa3b, v41
	v_exp_f32_e32 v140, v140
	v_and_b32_e32 v146, 0xffff0000, v146
	v_mul_f32_e32 v136, v136, v169
	v_rcp_f32_e32 v89, v89
	v_add_f32_e32 v140, 1.0, v140
	v_rcp_f32_e32 v140, v140
	v_add_f32_e32 v90, 1.0, v90
	v_rcp_f32_e32 v90, v90
	v_mul_f32_e32 v140, v140, v190
	v_exp_f32_e32 v140, v140
	v_fmamk_f32 v84, v84, 0xbfb8aa3b, v28
	v_exp_f32_e32 v84, v84
	v_sub_f32_e32 v141, 1.0, v140
	v_fma_f32 v140, -v140, v140, 1.0
	v_max_f32_e32 v140, 0, v140
	v_sqrt_f32_e32 v140, v140
	v_add_f32_e32 v84, 1.0, v84
	v_fmamk_f32 v91, v91, 0xbfb8aa3b, v47
	v_rcp_f32_e32 v84, v84
	v_mul_f32_e32 v137, v137, v140
	v_fmamk_f32 v140, v142, 0xbfb8aa3b, v42
	v_exp_f32_e32 v140, v140
	v_mul_f32_e32 v137, v137, v193
	v_exp_f32_e32 v91, v91
	v_mul_f32_e32 v84, v84, v188
	v_add_f32_e32 v140, 1.0, v140
	v_rcp_f32_e32 v140, v140
	v_add_f32_e32 v91, 1.0, v91
	v_rcp_f32_e32 v91, v91
	v_mul_f32_e32 v140, v140, v191
	v_exp_f32_e32 v140, v140
	v_exp_f32_e32 v84, v84
	v_fmamk_f32 v80, v80, 0xbfb8aa3b, v32
	v_sub_f32_e32 v142, 1.0, v140
	v_fma_f32 v140, -v140, v140, 1.0
	v_max_f32_e32 v140, 0, v140
	v_sqrt_f32_e32 v140, v140
	v_exp_f32_e32 v80, v80
	v_fmamk_f32 v81, v81, 0xbfb8aa3b, v33
	v_mul_f32_e32 v138, v138, v140
	v_fmamk_f32 v140, v143, 0xbfb8aa3b, v43
	v_exp_f32_e32 v140, v140
	v_mul_f32_e32 v138, v138, v194
	v_add_f32_e32 v80, 1.0, v80
	v_rcp_f32_e32 v80, v80
	v_add_f32_e32 v140, 1.0, v140
	v_rcp_f32_e32 v140, v140
	v_exp_f32_e32 v81, v81
	v_fmamk_f32 v76, v76, 0xbfb8aa3b, v40
	v_mul_f32_e32 v140, v140, v192
	v_exp_f32_e32 v140, v140
	v_add_f32_e32 v81, 1.0, v81
	v_rcp_f32_e32 v81, v81
	v_exp_f32_e32 v76, v76
	v_sub_f32_e32 v143, 1.0, v140
	v_fma_f32 v140, -v140, v140, 1.0
	v_max_f32_e32 v140, 0, v140
	v_sqrt_f32_e32 v140, v140
	v_add_f32_e32 v76, 1.0, v76
	v_rcp_f32_e32 v76, v76
	v_mul_f32_e32 v139, v139, v140
	v_sub_f32_e32 v140, 1.0, v132
	v_fma_f32 v132, -v132, v132, 1.0
	v_max_f32_e32 v132, 0, v132
	v_sqrt_f32_e32 v132, v132
	v_mul_f32_e32 v139, v139, v145
	v_mul_f32_e32 v76, v76, v187
	v_mul_f32_e32 v128, v128, v132
	v_mul_f32_e32 v145, v128, v195
	v_fmamk_f32 v128, v133, 0xbfb8aa3b, v29
	v_exp_f32_e32 v128, v128
	v_exp_f32_e32 v76, v76
	v_fmamk_f32 v72, v72, 0xbfb8aa3b, v44
	v_exp_f32_e32 v72, v72
	v_add_f32_e32 v128, 1.0, v128
	v_rcp_f32_e32 v128, v128
	v_add_f32_e32 v72, 1.0, v72
	v_rcp_f32_e32 v72, v72
	v_mul_f32_e32 v128, v128, v189
	v_exp_f32_e32 v128, v128
	v_fmamk_f32 v73, v73, 0xbfb8aa3b, v45
	v_exp_f32_e32 v73, v73
	v_sub_f32_e32 v132, 1.0, v128
	v_fma_f32 v128, -v128, v128, 1.0
	v_max_f32_e32 v128, 0, v128
	v_sqrt_f32_e32 v128, v128
	v_add_f32_e32 v73, 1.0, v73
	v_rcp_f32_e32 v73, v73
	v_fmamk_f32 v74, v74, 0xbfb8aa3b, v46
	v_mul_f32_e32 v128, v129, v128
	v_mul_f32_e32 v146, v128, v146
	v_fmamk_f32 v128, v134, 0xbfb8aa3b, v30
	v_exp_f32_e32 v128, v128
	v_fmamk_f32 v129, v130, 0xbfb8aa3b, v34
	v_exp_f32_e32 v129, v129
	v_add_f32_e32 v128, 1.0, v128
	v_rcp_f32_e32 v128, v128
	v_exp_f32_e32 v74, v74
	v_add_f32_e32 v129, 1.0, v129
	v_rcp_f32_e32 v129, v129
	v_mul_f32_e32 v128, v128, v150
	v_exp_f32_e32 v128, v128
	v_add_f32_e32 v74, 1.0, v74
	v_rcp_f32_e32 v74, v74
	v_sub_f32_e32 v133, 1.0, v128
	v_fma_f32 v128, -v128, v128, 1.0
	v_max_f32_e32 v128, 0, v128
	v_sqrt_f32_e32 v128, v128
	v_fmamk_f32 v68, v68, 0xbfb8aa3b, v28
	v_exp_f32_e32 v68, v68
	v_mul_f32_e32 v128, v129, v128
	v_mul_f32_e32 v134, v128, v196
	v_fmamk_f32 v128, v135, 0xbfb8aa3b, v31
	v_exp_f32_e32 v128, v128
	v_fmamk_f32 v129, v131, 0xbfb8aa3b, v35
	v_exp_f32_e32 v129, v129
	v_add_f32_e32 v128, 1.0, v128
	v_rcp_f32_e32 v128, v128
	v_add_f32_e32 v68, 1.0, v68
	v_add_f32_e32 v129, 1.0, v129
	v_rcp_f32_e32 v129, v129
	v_mul_f32_e32 v128, v128, v151
	v_exp_f32_e32 v128, v128
	v_fmamk_f32 v75, v75, 0xbfb8aa3b, v47
	v_rcp_f32_e32 v68, v68
	v_exp_f32_e32 v75, v75
	v_sub_f32_e32 v131, 1.0, v128
	v_fma_f32 v128, -v128, v128, 1.0
	v_max_f32_e32 v128, 0, v128
	v_sqrt_f32_e32 v128, v128
	v_mul_f32_e32 v68, v68, v188
	v_add_f32_e32 v75, 1.0, v75
	v_mul_f32_e32 v128, v129, v128
	v_mul_f32_e32 v135, v128, v144
	v_cvt_pk_bf16_f32 v128, v147, v141
	v_cvt_pk_bf16_f32 v129, v142, v143
	v_cvt_pk_bf16_f32 v130, v140, v132
	v_cvt_pk_bf16_f32 v131, v133, v131
	v_lshl_add_u64 v[132:133], s[20:21], 0, v[148:149]
	global_store_dwordx4 v[132:133], v[128:131], off sc0 sc1
	s_nop 1
	v_cvt_pk_bf16_f32 v128, v136, v137
	v_cvt_pk_bf16_f32 v129, v138, v139
	v_cvt_pk_bf16_f32 v130, v145, v146
	v_cvt_pk_bf16_f32 v131, v134, v135
	v_lshl_add_u64 v[132:133], s[34:35], 0, v[148:149]
	global_store_dwordx4 v[132:133], v[128:131], off sc0 sc1
	s_nop 1
	v_or_b32_e32 v128, 16, v168
	v_ashrrev_i32_e32 v129, 31, v128
	v_lshlrev_b64 v[128:129], 10, v[128:129]
	v_lshl_add_u64 v[128:129], v[128:129], 0, v[166:167]
	v_lshlrev_b64 v[128:129], 1, v[128:129]
	v_lshl_add_u64 v[130:131], s[30:31], 0, v[128:129]
	global_load_dwordx4 v[130:133], v[130:131], off
	v_rcp_f32_e32 v75, v75
	v_exp_f32_e32 v68, v68
	v_fmamk_f32 v64, v64, 0xbfb8aa3b, v32
	v_exp_f32_e32 v64, v64
	v_fmamk_f32 v65, v65, 0xbfb8aa3b, v33
	v_exp_f32_e32 v65, v65
	v_add_f32_e32 v64, 1.0, v64
	v_rcp_f32_e32 v64, v64
	v_add_f32_e32 v65, 1.0, v65
	v_rcp_f32_e32 v65, v65
	v_fmamk_f32 v60, v60, 0xbfb8aa3b, v40
	v_exp_f32_e32 v60, v60
	v_fmamk_f32 v56, v56, 0xbfb8aa3b, v44
	v_exp_f32_e32 v56, v56
	v_add_f32_e32 v60, 1.0, v60
	v_rcp_f32_e32 v60, v60
	v_add_f32_e32 v56, 1.0, v56
	v_rcp_f32_e32 v56, v56
	v_mul_f32_e32 v60, v60, v187
	v_exp_f32_e32 v60, v60
	v_fmamk_f32 v57, v57, 0xbfb8aa3b, v45
	v_exp_f32_e32 v57, v57
	v_fmamk_f32 v58, v58, 0xbfb8aa3b, v46
	v_exp_f32_e32 v58, v58
	v_add_f32_e32 v57, 1.0, v57
	v_rcp_f32_e32 v57, v57
	v_add_f32_e32 v58, 1.0, v58
	v_rcp_f32_e32 v58, v58
	v_fmamk_f32 v52, v52, 0xbfb8aa3b, v28
	v_exp_f32_e32 v52, v52
	v_fmamk_f32 v59, v59, 0xbfb8aa3b, v47
	v_exp_f32_e32 v59, v59
	v_add_f32_e32 v52, 1.0, v52
	v_rcp_f32_e32 v52, v52
	v_add_f32_e32 v59, 1.0, v59
	v_rcp_f32_e32 v59, v59
	v_mul_f32_e32 v52, v52, v188
	v_exp_f32_e32 v52, v52
	v_fmamk_f32 v48, v48, 0xbfb8aa3b, v32
	v_exp_f32_e32 v48, v48
	v_fmamk_f32 v49, v49, 0xbfb8aa3b, v33
	v_exp_f32_e32 v49, v49
	v_add_f32_e32 v48, 1.0, v48
	v_rcp_f32_e32 v48, v48
	v_add_f32_e32 v49, 1.0, v49
	v_rcp_f32_e32 v49, v49
	v_fmamk_f32 v36, v36, 0xbfb8aa3b, v40
	v_exp_f32_e32 v36, v36
	v_fmamk_f32 v24, v24, 0xbfb8aa3b, v44
	v_exp_f32_e32 v24, v24
	v_add_f32_e32 v36, 1.0, v36
	v_rcp_f32_e32 v36, v36
	v_add_f32_e32 v24, 1.0, v24
	v_rcp_f32_e32 v24, v24
	v_mul_f32_e32 v36, v36, v187
	v_exp_f32_e32 v36, v36
	v_fmamk_f32 v25, v25, 0xbfb8aa3b, v45
	v_exp_f32_e32 v25, v25
	v_fmamk_f32 v26, v26, 0xbfb8aa3b, v46
	v_exp_f32_e32 v26, v26
	v_add_f32_e32 v25, 1.0, v25
	v_rcp_f32_e32 v25, v25
	s_waitcnt vmcnt(0)
	v_lshlrev_b32_e32 v134, 16, v130
	v_and_b32_e32 v135, 0xffff0000, v130
	v_lshlrev_b32_e32 v138, 16, v133
	v_and_b32_e32 v130, 0xffff0000, v133
	v_sub_f32_e32 v133, 1.0, v124
	v_fma_f32 v124, -v124, v124, 1.0
	v_max_f32_e32 v124, 0, v124
	v_sqrt_f32_e32 v124, v124
	v_lshlrev_b32_e32 v136, 16, v131
	v_and_b32_e32 v131, 0xffff0000, v131
	v_lshlrev_b32_e32 v137, 16, v132
	v_mul_f32_e32 v120, v120, v124
	v_fmamk_f32 v124, v125, 0xbfb8aa3b, v41
	v_exp_f32_e32 v124, v124
	v_and_b32_e32 v132, 0xffff0000, v132
	v_mul_f32_e32 v120, v120, v134
	v_add_f32_e32 v26, 1.0, v26
	v_add_f32_e32 v124, 1.0, v124
	v_rcp_f32_e32 v124, v124
	v_rcp_f32_e32 v26, v26
	v_fmamk_f32 v20, v20, 0xbfb8aa3b, v28
	v_mul_f32_e32 v124, v124, v190
	v_exp_f32_e32 v124, v124
	v_exp_f32_e32 v20, v20
	v_fmamk_f32 v27, v27, 0xbfb8aa3b, v47
	v_sub_f32_e32 v125, 1.0, v124
	v_fma_f32 v124, -v124, v124, 1.0
	v_max_f32_e32 v124, 0, v124
	v_sqrt_f32_e32 v124, v124
	v_add_f32_e32 v20, 1.0, v20
	v_rcp_f32_e32 v20, v20
	v_exp_f32_e32 v27, v27
	v_mul_f32_e32 v121, v121, v124
	v_fmamk_f32 v124, v126, 0xbfb8aa3b, v42
	v_exp_f32_e32 v124, v124
	v_mul_f32_e32 v121, v121, v135
	v_mul_f32_e32 v20, v20, v188
	v_add_f32_e32 v27, 1.0, v27
	v_add_f32_e32 v124, 1.0, v124
	v_rcp_f32_e32 v124, v124
	v_rcp_f32_e32 v27, v27
	v_mul_f32_e32 v124, v124, v191
	v_exp_f32_e32 v124, v124
	v_exp_f32_e32 v20, v20
	v_fmamk_f32 v16, v16, 0xbfb8aa3b, v32
	v_exp_f32_e32 v16, v16
	v_sub_f32_e32 v126, 1.0, v124
	v_fma_f32 v124, -v124, v124, 1.0
	v_max_f32_e32 v124, 0, v124
	v_sqrt_f32_e32 v124, v124
	v_add_f32_e32 v16, 1.0, v16
	v_rcp_f32_e32 v16, v16
	v_mul_f32_e32 v122, v122, v124
	v_fmamk_f32 v124, v127, 0xbfb8aa3b, v43
	v_exp_f32_e32 v124, v124
	v_mul_f32_e32 v122, v122, v136
	v_fmamk_f32 v17, v17, 0xbfb8aa3b, v33
	v_exp_f32_e32 v17, v17
	v_add_f32_e32 v124, 1.0, v124
	v_rcp_f32_e32 v124, v124
	v_add_f32_e32 v17, 1.0, v17
	v_rcp_f32_e32 v17, v17
	v_mul_f32_e32 v124, v124, v192
	v_exp_f32_e32 v124, v124
	v_fmamk_f32 v12, v12, 0xbfb8aa3b, v40
	v_exp_f32_e32 v12, v12
	v_sub_f32_e32 v127, 1.0, v124
	v_fma_f32 v124, -v124, v124, 1.0
	v_max_f32_e32 v124, 0, v124
	v_sqrt_f32_e32 v124, v124
	v_add_f32_e32 v12, 1.0, v12
	v_rcp_f32_e32 v12, v12
	v_fmamk_f32 v8, v8, 0xbfb8aa3b, v44
	v_mul_f32_e32 v123, v123, v124
	v_sub_f32_e32 v124, 1.0, v116
	v_fma_f32 v116, -v116, v116, 1.0
	v_max_f32_e32 v116, 0, v116
	v_sqrt_f32_e32 v116, v116
	v_mul_f32_e32 v123, v123, v131
	v_mul_f32_e32 v12, v12, v187
	v_mul_f32_e32 v112, v112, v116
	v_mul_f32_e32 v131, v112, v137
	v_fmamk_f32 v112, v117, 0xbfb8aa3b, v29
	v_exp_f32_e32 v112, v112
	v_exp_f32_e32 v12, v12
	v_exp_f32_e32 v8, v8
	v_add_f32_e32 v112, 1.0, v112
	v_rcp_f32_e32 v112, v112
	v_add_f32_e32 v8, 1.0, v8
	v_rcp_f32_e32 v8, v8
	v_fmamk_f32 v9, v9, 0xbfb8aa3b, v45
	v_mul_f32_e32 v112, v112, v189
	v_exp_f32_e32 v112, v112
	v_exp_f32_e32 v9, v9
	v_fmamk_f32 v10, v10, 0xbfb8aa3b, v46
	v_sub_f32_e32 v116, 1.0, v112
	v_fma_f32 v112, -v112, v112, 1.0
	v_max_f32_e32 v112, 0, v112
	v_sqrt_f32_e32 v112, v112
	v_add_f32_e32 v9, 1.0, v9
	v_rcp_f32_e32 v9, v9
	v_exp_f32_e32 v10, v10
	v_mul_f32_e32 v112, v113, v112
	v_mul_f32_e32 v132, v112, v132
	v_fmamk_f32 v112, v118, 0xbfb8aa3b, v30
	v_exp_f32_e32 v112, v112
	v_fmamk_f32 v113, v114, 0xbfb8aa3b, v34
	v_exp_f32_e32 v113, v113
	v_add_f32_e32 v112, 1.0, v112
	v_rcp_f32_e32 v112, v112
	v_add_f32_e32 v10, 1.0, v10
	v_add_f32_e32 v113, 1.0, v113
	v_rcp_f32_e32 v113, v113
	v_mul_f32_e32 v112, v112, v150
	v_exp_f32_e32 v112, v112
	v_rcp_f32_e32 v10, v10
	v_fmamk_f32 v4, v4, 0xbfb8aa3b, v28
	v_sub_f32_e32 v117, 1.0, v112
	v_fma_f32 v112, -v112, v112, 1.0
	v_max_f32_e32 v112, 0, v112
	v_sqrt_f32_e32 v112, v112
	v_exp_f32_e32 v4, v4
	v_fmamk_f32 v11, v11, 0xbfb8aa3b, v47
	v_mul_f32_e32 v112, v113, v112
	v_mul_f32_e32 v118, v112, v138
	v_fmamk_f32 v112, v119, 0xbfb8aa3b, v31
	v_exp_f32_e32 v112, v112
	v_fmamk_f32 v113, v115, 0xbfb8aa3b, v35
	v_exp_f32_e32 v113, v113
	v_add_f32_e32 v112, 1.0, v112
	v_rcp_f32_e32 v112, v112
	v_add_f32_e32 v4, 1.0, v4
	v_add_f32_e32 v113, 1.0, v113
	v_rcp_f32_e32 v113, v113
	v_mul_f32_e32 v112, v112, v151
	v_exp_f32_e32 v112, v112
	v_rcp_f32_e32 v4, v4
	v_exp_f32_e32 v11, v11
	v_sub_f32_e32 v115, 1.0, v112
	v_fma_f32 v112, -v112, v112, 1.0
	v_max_f32_e32 v112, 0, v112
	v_sqrt_f32_e32 v112, v112
	v_mul_f32_e32 v4, v4, v188
	v_add_f32_e32 v11, 1.0, v11
	v_mul_f32_e32 v112, v113, v112
	v_mul_f32_e32 v119, v112, v130
	v_cvt_pk_bf16_f32 v112, v133, v125
	v_cvt_pk_bf16_f32 v113, v126, v127
	v_cvt_pk_bf16_f32 v114, v124, v116
	v_cvt_pk_bf16_f32 v115, v117, v115
	v_lshl_add_u64 v[116:117], s[20:21], 0, v[128:129]
	global_store_dwordx4 v[116:117], v[112:115], off sc0 sc1
	s_nop 1
	v_cvt_pk_bf16_f32 v112, v120, v121
	v_cvt_pk_bf16_f32 v113, v122, v123
	v_cvt_pk_bf16_f32 v114, v131, v132
	v_cvt_pk_bf16_f32 v115, v118, v119
	v_lshl_add_u64 v[116:117], s[34:35], 0, v[128:129]
	global_store_dwordx4 v[116:117], v[112:115], off sc0 sc1
	s_nop 1
	v_or_b32_e32 v112, 32, v168
	v_ashrrev_i32_e32 v113, 31, v112
	v_lshlrev_b64 v[112:113], 10, v[112:113]
	v_lshl_add_u64 v[112:113], v[112:113], 0, v[166:167]
	v_lshlrev_b64 v[112:113], 1, v[112:113]
	v_lshl_add_u64 v[114:115], s[30:31], 0, v[112:113]
	global_load_dwordx4 v[114:117], v[114:115], off
	v_rcp_f32_e32 v11, v11
	v_exp_f32_e32 v4, v4
	v_fmamk_f32 v0, v0, 0xbfb8aa3b, v32
	v_exp_f32_e32 v0, v0
	v_fmamk_f32 v1, v1, 0xbfb8aa3b, v33
	v_exp_f32_e32 v1, v1
	v_add_f32_e32 v0, 1.0, v0
	v_rcp_f32_e32 v0, v0
	v_add_f32_e32 v1, 1.0, v1
	v_rcp_f32_e32 v1, v1
	s_waitcnt vmcnt(0)
	v_lshlrev_b32_e32 v118, 16, v114
	v_and_b32_e32 v119, 0xffff0000, v114
	v_lshlrev_b32_e32 v122, 16, v117
	v_and_b32_e32 v114, 0xffff0000, v117
	v_sub_f32_e32 v117, 1.0, v108
	v_fma_f32 v108, -v108, v108, 1.0
	v_max_f32_e32 v108, 0, v108
	v_sqrt_f32_e32 v108, v108
	v_lshlrev_b32_e32 v120, 16, v115
	v_and_b32_e32 v115, 0xffff0000, v115
	v_lshlrev_b32_e32 v121, 16, v116
	v_mul_f32_e32 v104, v104, v108
	v_fmamk_f32 v108, v109, 0xbfb8aa3b, v41
	v_exp_f32_e32 v108, v108
	v_and_b32_e32 v116, 0xffff0000, v116
	v_mul_f32_e32 v104, v104, v118
	v_add_f32_e32 v108, 1.0, v108
	v_rcp_f32_e32 v108, v108
	s_nop 0
	v_mul_f32_e32 v108, v108, v190
	v_exp_f32_e32 v108, v108
	s_nop 0
	v_sub_f32_e32 v109, 1.0, v108
	v_fma_f32 v108, -v108, v108, 1.0
	v_max_f32_e32 v108, 0, v108
	v_sqrt_f32_e32 v108, v108
	s_nop 0
	v_mul_f32_e32 v105, v105, v108
	v_fmamk_f32 v108, v110, 0xbfb8aa3b, v42
	v_exp_f32_e32 v108, v108
	v_mul_f32_e32 v105, v105, v119
	v_add_f32_e32 v108, 1.0, v108
	v_rcp_f32_e32 v108, v108
	s_nop 0
	v_mul_f32_e32 v108, v108, v191
	v_exp_f32_e32 v108, v108
	s_nop 0
	v_sub_f32_e32 v110, 1.0, v108
	v_fma_f32 v108, -v108, v108, 1.0
	v_max_f32_e32 v108, 0, v108
	v_sqrt_f32_e32 v108, v108
	s_nop 0
	v_mul_f32_e32 v106, v106, v108
	v_fmamk_f32 v108, v111, 0xbfb8aa3b, v43
	v_exp_f32_e32 v108, v108
	v_mul_f32_e32 v106, v106, v120
	v_add_f32_e32 v108, 1.0, v108
	v_rcp_f32_e32 v108, v108
	s_nop 0
	v_mul_f32_e32 v108, v108, v192
	v_exp_f32_e32 v108, v108
	s_nop 0
	v_sub_f32_e32 v111, 1.0, v108
	v_fma_f32 v108, -v108, v108, 1.0
	v_max_f32_e32 v108, 0, v108
	v_sqrt_f32_e32 v108, v108
	s_nop 0
	v_mul_f32_e32 v107, v107, v108
	v_sub_f32_e32 v108, 1.0, v100
	v_fma_f32 v100, -v100, v100, 1.0
	v_max_f32_e32 v100, 0, v100
	v_sqrt_f32_e32 v100, v100
	v_mul_f32_e32 v107, v107, v115
	v_mul_f32_e32 v96, v96, v100
	v_mul_f32_e32 v115, v96, v121
	v_fmamk_f32 v96, v101, 0xbfb8aa3b, v29
	v_exp_f32_e32 v96, v96
	s_nop 0
	v_add_f32_e32 v96, 1.0, v96
	v_rcp_f32_e32 v96, v96
	s_nop 0
	v_mul_f32_e32 v96, v96, v189
	v_exp_f32_e32 v96, v96
	s_nop 0
	v_sub_f32_e32 v100, 1.0, v96
	v_fma_f32 v96, -v96, v96, 1.0
	v_max_f32_e32 v96, 0, v96
	v_sqrt_f32_e32 v96, v96
	s_nop 0
	v_mul_f32_e32 v96, v97, v96
	v_mul_f32_e32 v116, v96, v116
	v_fmamk_f32 v96, v102, 0xbfb8aa3b, v30
	v_exp_f32_e32 v96, v96
	v_fmamk_f32 v97, v98, 0xbfb8aa3b, v34
	v_exp_f32_e32 v97, v97
	v_add_f32_e32 v96, 1.0, v96
	v_rcp_f32_e32 v96, v96
	v_add_f32_e32 v97, 1.0, v97
	v_rcp_f32_e32 v97, v97
	v_mul_f32_e32 v96, v96, v150
	v_exp_f32_e32 v96, v96
	s_nop 0
	v_sub_f32_e32 v101, 1.0, v96
	v_fma_f32 v96, -v96, v96, 1.0
	v_max_f32_e32 v96, 0, v96
	v_sqrt_f32_e32 v96, v96
	s_nop 0
	v_mul_f32_e32 v96, v97, v96
	v_mul_f32_e32 v102, v96, v122
	v_fmamk_f32 v96, v103, 0xbfb8aa3b, v31
	v_exp_f32_e32 v96, v96
	v_fmamk_f32 v97, v99, 0xbfb8aa3b, v35
	v_exp_f32_e32 v97, v97
	v_add_f32_e32 v96, 1.0, v96
	v_rcp_f32_e32 v96, v96
	v_add_f32_e32 v97, 1.0, v97
	v_rcp_f32_e32 v97, v97
	v_mul_f32_e32 v96, v96, v151
	v_exp_f32_e32 v96, v96
	s_nop 0
	v_sub_f32_e32 v99, 1.0, v96
	v_fma_f32 v96, -v96, v96, 1.0
	v_max_f32_e32 v96, 0, v96
	v_sqrt_f32_e32 v96, v96
	s_nop 0
	v_mul_f32_e32 v96, v97, v96
	v_mul_f32_e32 v103, v96, v114
	v_cvt_pk_bf16_f32 v96, v117, v109
	v_cvt_pk_bf16_f32 v97, v110, v111
	v_cvt_pk_bf16_f32 v98, v108, v100
	v_cvt_pk_bf16_f32 v99, v101, v99
	v_lshl_add_u64 v[100:101], s[20:21], 0, v[112:113]
	global_store_dwordx4 v[100:101], v[96:99], off sc0 sc1
	s_nop 1
	v_cvt_pk_bf16_f32 v96, v104, v105
	v_cvt_pk_bf16_f32 v97, v106, v107
	v_cvt_pk_bf16_f32 v98, v115, v116
	v_cvt_pk_bf16_f32 v99, v102, v103
	v_lshl_add_u64 v[100:101], s[34:35], 0, v[112:113]
	global_store_dwordx4 v[100:101], v[96:99], off sc0 sc1
	s_nop 1
	v_or_b32_e32 v96, 48, v168
	v_ashrrev_i32_e32 v97, 31, v96
	v_lshlrev_b64 v[96:97], 10, v[96:97]
	v_lshl_add_u64 v[96:97], v[96:97], 0, v[166:167]
	v_lshlrev_b64 v[96:97], 1, v[96:97]
	v_lshl_add_u64 v[98:99], s[30:31], 0, v[96:97]
	global_load_dwordx4 v[98:101], v[98:99], off
	s_waitcnt vmcnt(0)
	v_lshlrev_b32_e32 v102, 16, v98
	v_and_b32_e32 v103, 0xffff0000, v98
	v_lshlrev_b32_e32 v106, 16, v101
	v_and_b32_e32 v98, 0xffff0000, v101
	v_sub_f32_e32 v101, 1.0, v92
	v_fma_f32 v92, -v92, v92, 1.0
	v_max_f32_e32 v92, 0, v92
	v_sqrt_f32_e32 v92, v92
	v_lshlrev_b32_e32 v104, 16, v99
	v_and_b32_e32 v99, 0xffff0000, v99
	v_lshlrev_b32_e32 v105, 16, v100
	v_mul_f32_e32 v88, v88, v92
	v_fmamk_f32 v92, v93, 0xbfb8aa3b, v41
	v_exp_f32_e32 v92, v92
	v_and_b32_e32 v100, 0xffff0000, v100
	v_mul_f32_e32 v88, v88, v102
	v_add_f32_e32 v92, 1.0, v92
	v_rcp_f32_e32 v92, v92
	s_nop 0
	v_mul_f32_e32 v92, v92, v190
	v_exp_f32_e32 v92, v92
	s_nop 0
	v_sub_f32_e32 v93, 1.0, v92
	v_fma_f32 v92, -v92, v92, 1.0
	v_max_f32_e32 v92, 0, v92
	v_sqrt_f32_e32 v92, v92
	s_nop 0
	v_mul_f32_e32 v89, v89, v92
	v_fmamk_f32 v92, v94, 0xbfb8aa3b, v42
	v_exp_f32_e32 v92, v92
	v_mul_f32_e32 v89, v89, v103
	v_add_f32_e32 v92, 1.0, v92
	v_rcp_f32_e32 v92, v92
	s_nop 0
	v_mul_f32_e32 v92, v92, v191
	v_exp_f32_e32 v92, v92
	s_nop 0
	v_sub_f32_e32 v94, 1.0, v92
	v_fma_f32 v92, -v92, v92, 1.0
	v_max_f32_e32 v92, 0, v92
	v_sqrt_f32_e32 v92, v92
	s_nop 0
	v_mul_f32_e32 v90, v90, v92
	v_fmamk_f32 v92, v95, 0xbfb8aa3b, v43
	v_exp_f32_e32 v92, v92
	v_mul_f32_e32 v90, v90, v104
	v_add_f32_e32 v92, 1.0, v92
	v_rcp_f32_e32 v92, v92
	s_nop 0
	v_mul_f32_e32 v92, v92, v192
	v_exp_f32_e32 v92, v92
	s_nop 0
	v_sub_f32_e32 v95, 1.0, v92
	v_fma_f32 v92, -v92, v92, 1.0
	v_max_f32_e32 v92, 0, v92
	v_sqrt_f32_e32 v92, v92
	s_nop 0
	v_mul_f32_e32 v91, v91, v92
	v_sub_f32_e32 v92, 1.0, v84
	v_fma_f32 v84, -v84, v84, 1.0
	v_max_f32_e32 v84, 0, v84
	v_sqrt_f32_e32 v84, v84
	v_mul_f32_e32 v91, v91, v99
	v_mul_f32_e32 v80, v80, v84
	v_mul_f32_e32 v99, v80, v105
	v_fmamk_f32 v80, v85, 0xbfb8aa3b, v29
	v_exp_f32_e32 v80, v80
	s_nop 0
	v_add_f32_e32 v80, 1.0, v80
	v_rcp_f32_e32 v80, v80
	s_nop 0
	v_mul_f32_e32 v80, v80, v189
	v_exp_f32_e32 v80, v80
	s_nop 0
	v_sub_f32_e32 v84, 1.0, v80
	v_fma_f32 v80, -v80, v80, 1.0
	v_max_f32_e32 v80, 0, v80
	v_sqrt_f32_e32 v80, v80
	s_nop 0
	v_mul_f32_e32 v80, v81, v80
	v_mul_f32_e32 v100, v80, v100
	v_fmamk_f32 v80, v86, 0xbfb8aa3b, v30
	v_exp_f32_e32 v80, v80
	v_fmamk_f32 v81, v82, 0xbfb8aa3b, v34
	v_exp_f32_e32 v81, v81
	v_add_f32_e32 v80, 1.0, v80
	v_rcp_f32_e32 v80, v80
	v_add_f32_e32 v81, 1.0, v81
	v_rcp_f32_e32 v81, v81
	v_mul_f32_e32 v80, v80, v150
	v_exp_f32_e32 v80, v80
	s_nop 0
	v_sub_f32_e32 v85, 1.0, v80
	v_fma_f32 v80, -v80, v80, 1.0
	v_max_f32_e32 v80, 0, v80
	v_sqrt_f32_e32 v80, v80
	s_nop 0
	v_mul_f32_e32 v80, v81, v80
	v_mul_f32_e32 v86, v80, v106
	v_fmamk_f32 v80, v87, 0xbfb8aa3b, v31
	v_exp_f32_e32 v80, v80
	v_fmamk_f32 v81, v83, 0xbfb8aa3b, v35
	v_exp_f32_e32 v81, v81
	v_add_f32_e32 v80, 1.0, v80
	v_rcp_f32_e32 v80, v80
	v_add_f32_e32 v81, 1.0, v81
	v_rcp_f32_e32 v81, v81
	v_mul_f32_e32 v80, v80, v151
	v_exp_f32_e32 v80, v80
	s_nop 0
	v_sub_f32_e32 v83, 1.0, v80
	v_fma_f32 v80, -v80, v80, 1.0
	v_max_f32_e32 v80, 0, v80
	v_sqrt_f32_e32 v80, v80
	s_nop 0
	v_mul_f32_e32 v80, v81, v80
	v_mul_f32_e32 v87, v80, v98
	v_cvt_pk_bf16_f32 v80, v101, v93
	v_cvt_pk_bf16_f32 v81, v94, v95
	v_cvt_pk_bf16_f32 v82, v92, v84
	v_cvt_pk_bf16_f32 v83, v85, v83
	v_lshl_add_u64 v[84:85], s[20:21], 0, v[96:97]
	global_store_dwordx4 v[84:85], v[80:83], off sc0 sc1
	s_nop 1
	v_cvt_pk_bf16_f32 v80, v88, v89
	v_cvt_pk_bf16_f32 v81, v90, v91
	v_cvt_pk_bf16_f32 v82, v99, v100
	v_cvt_pk_bf16_f32 v83, v86, v87
	v_lshl_add_u64 v[84:85], s[34:35], 0, v[96:97]
	global_store_dwordx4 v[84:85], v[80:83], off sc0 sc1
	s_nop 1
	v_lshl_add_u64 v[80:81], v[148:149], 0, s[8:9]
	v_lshl_add_u64 v[82:83], s[30:31], 0, v[80:81]
	global_load_dwordx4 v[82:85], v[82:83], off
	s_mov_b64 s[8:9], 0x48000
	s_waitcnt vmcnt(0)
	v_lshlrev_b32_e32 v86, 16, v82
	v_and_b32_e32 v87, 0xffff0000, v82
	v_lshlrev_b32_e32 v90, 16, v85
	v_and_b32_e32 v82, 0xffff0000, v85
	v_sub_f32_e32 v85, 1.0, v76
	v_fma_f32 v76, -v76, v76, 1.0
	v_max_f32_e32 v76, 0, v76
	v_sqrt_f32_e32 v76, v76
	v_lshlrev_b32_e32 v88, 16, v83
	v_and_b32_e32 v83, 0xffff0000, v83
	v_lshlrev_b32_e32 v89, 16, v84
	v_mul_f32_e32 v72, v72, v76
	v_fmamk_f32 v76, v77, 0xbfb8aa3b, v41
	v_exp_f32_e32 v76, v76
	v_and_b32_e32 v84, 0xffff0000, v84
	v_mul_f32_e32 v72, v72, v86
	v_add_f32_e32 v76, 1.0, v76
	v_rcp_f32_e32 v76, v76
	s_nop 0
	v_mul_f32_e32 v76, v76, v190
	v_exp_f32_e32 v76, v76
	s_nop 0
	v_sub_f32_e32 v77, 1.0, v76
	v_fma_f32 v76, -v76, v76, 1.0
	v_max_f32_e32 v76, 0, v76
	v_sqrt_f32_e32 v76, v76
	s_nop 0
	v_mul_f32_e32 v73, v73, v76
	v_fmamk_f32 v76, v78, 0xbfb8aa3b, v42
	v_exp_f32_e32 v76, v76
	v_mul_f32_e32 v73, v73, v87
	v_add_f32_e32 v76, 1.0, v76
	v_rcp_f32_e32 v76, v76
	s_nop 0
	v_mul_f32_e32 v76, v76, v191
	v_exp_f32_e32 v76, v76
	s_nop 0
	v_sub_f32_e32 v78, 1.0, v76
	v_fma_f32 v76, -v76, v76, 1.0
	v_max_f32_e32 v76, 0, v76
	v_sqrt_f32_e32 v76, v76
	s_nop 0
	v_mul_f32_e32 v74, v74, v76
	v_fmamk_f32 v76, v79, 0xbfb8aa3b, v43
	v_exp_f32_e32 v76, v76
	v_mul_f32_e32 v74, v74, v88
	v_add_f32_e32 v76, 1.0, v76
	v_rcp_f32_e32 v76, v76
	s_nop 0
	v_mul_f32_e32 v76, v76, v192
	v_exp_f32_e32 v76, v76
	s_nop 0
	v_sub_f32_e32 v79, 1.0, v76
	v_fma_f32 v76, -v76, v76, 1.0
	v_max_f32_e32 v76, 0, v76
	v_sqrt_f32_e32 v76, v76
	s_nop 0
	v_mul_f32_e32 v75, v75, v76
	v_sub_f32_e32 v76, 1.0, v68
	v_fma_f32 v68, -v68, v68, 1.0
	v_max_f32_e32 v68, 0, v68
	v_sqrt_f32_e32 v68, v68
	v_mul_f32_e32 v75, v75, v83
	v_mul_f32_e32 v64, v64, v68
	v_mul_f32_e32 v83, v64, v89
	v_fmamk_f32 v64, v69, 0xbfb8aa3b, v29
	v_exp_f32_e32 v64, v64
	s_nop 0
	v_add_f32_e32 v64, 1.0, v64
	v_rcp_f32_e32 v64, v64
	s_nop 0
	v_mul_f32_e32 v64, v64, v189
	v_exp_f32_e32 v64, v64
	s_nop 0
	v_sub_f32_e32 v68, 1.0, v64
	v_fma_f32 v64, -v64, v64, 1.0
	v_max_f32_e32 v64, 0, v64
	v_sqrt_f32_e32 v64, v64
	s_nop 0
	v_mul_f32_e32 v64, v65, v64
	v_mul_f32_e32 v84, v64, v84
	v_fmamk_f32 v64, v70, 0xbfb8aa3b, v30
	v_exp_f32_e32 v64, v64
	v_fmamk_f32 v65, v66, 0xbfb8aa3b, v34
	v_exp_f32_e32 v65, v65
	v_add_f32_e32 v64, 1.0, v64
	v_rcp_f32_e32 v64, v64
	v_add_f32_e32 v65, 1.0, v65
	v_rcp_f32_e32 v65, v65
	v_mul_f32_e32 v64, v64, v150
	v_exp_f32_e32 v64, v64
	s_nop 0
	v_sub_f32_e32 v69, 1.0, v64
	v_fma_f32 v64, -v64, v64, 1.0
	v_max_f32_e32 v64, 0, v64
	v_sqrt_f32_e32 v64, v64
	s_nop 0
	v_mul_f32_e32 v64, v65, v64
	v_mul_f32_e32 v70, v64, v90
	v_fmamk_f32 v64, v71, 0xbfb8aa3b, v31
	v_exp_f32_e32 v64, v64
	v_fmamk_f32 v65, v67, 0xbfb8aa3b, v35
	v_exp_f32_e32 v65, v65
	v_add_f32_e32 v64, 1.0, v64
	v_rcp_f32_e32 v64, v64
	v_add_f32_e32 v65, 1.0, v65
	v_rcp_f32_e32 v65, v65
	v_mul_f32_e32 v64, v64, v151
	v_exp_f32_e32 v64, v64
	s_nop 0
	v_sub_f32_e32 v67, 1.0, v64
	v_fma_f32 v64, -v64, v64, 1.0
	v_max_f32_e32 v64, 0, v64
	v_sqrt_f32_e32 v64, v64
	s_nop 0
	v_mul_f32_e32 v64, v65, v64
	v_mul_f32_e32 v71, v64, v82
	v_cvt_pk_bf16_f32 v64, v85, v77
	v_cvt_pk_bf16_f32 v65, v78, v79
	v_cvt_pk_bf16_f32 v66, v76, v68
	v_cvt_pk_bf16_f32 v67, v69, v67
	v_lshl_add_u64 v[68:69], s[20:21], 0, v[80:81]
	global_store_dwordx4 v[68:69], v[64:67], off sc0 sc1
	s_nop 1
	v_cvt_pk_bf16_f32 v64, v72, v73
	v_cvt_pk_bf16_f32 v65, v74, v75
	v_cvt_pk_bf16_f32 v66, v83, v84
	v_cvt_pk_bf16_f32 v67, v70, v71
	v_lshl_add_u64 v[68:69], s[34:35], 0, v[80:81]
	global_store_dwordx4 v[68:69], v[64:67], off sc0 sc1
	s_nop 1
	v_lshl_add_u64 v[64:65], v[148:149], 0, s[8:9]
	v_lshl_add_u64 v[66:67], s[30:31], 0, v[64:65]
	global_load_dwordx4 v[66:69], v[66:67], off
	s_mov_b64 s[8:9], 0x50000
	s_waitcnt vmcnt(0)
	v_lshlrev_b32_e32 v70, 16, v66
	v_and_b32_e32 v71, 0xffff0000, v66
	v_lshlrev_b32_e32 v74, 16, v69
	v_and_b32_e32 v66, 0xffff0000, v69
	v_sub_f32_e32 v69, 1.0, v60
	v_fma_f32 v60, -v60, v60, 1.0
	v_max_f32_e32 v60, 0, v60
	v_sqrt_f32_e32 v60, v60
	v_lshlrev_b32_e32 v72, 16, v67
	v_and_b32_e32 v67, 0xffff0000, v67
	v_lshlrev_b32_e32 v73, 16, v68
	v_mul_f32_e32 v56, v56, v60
	v_fmamk_f32 v60, v61, 0xbfb8aa3b, v41
	v_exp_f32_e32 v60, v60
	v_and_b32_e32 v68, 0xffff0000, v68
	v_mul_f32_e32 v56, v56, v70
	v_add_f32_e32 v60, 1.0, v60
	v_rcp_f32_e32 v60, v60
	s_nop 0
	v_mul_f32_e32 v60, v60, v190
	v_exp_f32_e32 v60, v60
	s_nop 0
	v_sub_f32_e32 v61, 1.0, v60
	v_fma_f32 v60, -v60, v60, 1.0
	v_max_f32_e32 v60, 0, v60
	v_sqrt_f32_e32 v60, v60
	s_nop 0
	v_mul_f32_e32 v57, v57, v60
	v_fmamk_f32 v60, v62, 0xbfb8aa3b, v42
	v_exp_f32_e32 v60, v60
	v_mul_f32_e32 v57, v57, v71
	v_add_f32_e32 v60, 1.0, v60
	v_rcp_f32_e32 v60, v60
	s_nop 0
	v_mul_f32_e32 v60, v60, v191
	v_exp_f32_e32 v60, v60
	s_nop 0
	v_sub_f32_e32 v62, 1.0, v60
	v_fma_f32 v60, -v60, v60, 1.0
	v_max_f32_e32 v60, 0, v60
	v_sqrt_f32_e32 v60, v60
	s_nop 0
	v_mul_f32_e32 v58, v58, v60
	v_fmamk_f32 v60, v63, 0xbfb8aa3b, v43
	v_exp_f32_e32 v60, v60
	v_mul_f32_e32 v58, v58, v72
	v_add_f32_e32 v60, 1.0, v60
	v_rcp_f32_e32 v60, v60
	s_nop 0
	v_mul_f32_e32 v60, v60, v192
	v_exp_f32_e32 v60, v60
	s_nop 0
	v_sub_f32_e32 v63, 1.0, v60
	v_fma_f32 v60, -v60, v60, 1.0
	v_max_f32_e32 v60, 0, v60
	v_sqrt_f32_e32 v60, v60
	s_nop 0
	v_mul_f32_e32 v59, v59, v60
	v_sub_f32_e32 v60, 1.0, v52
	v_fma_f32 v52, -v52, v52, 1.0
	v_max_f32_e32 v52, 0, v52
	v_sqrt_f32_e32 v52, v52
	v_mul_f32_e32 v59, v59, v67
	v_mul_f32_e32 v48, v48, v52
	v_mul_f32_e32 v67, v48, v73
	v_fmamk_f32 v48, v53, 0xbfb8aa3b, v29
	v_exp_f32_e32 v48, v48
	s_nop 0
	v_add_f32_e32 v48, 1.0, v48
	v_rcp_f32_e32 v48, v48
	s_nop 0
	v_mul_f32_e32 v48, v48, v189
	v_exp_f32_e32 v48, v48
	s_nop 0
	v_sub_f32_e32 v52, 1.0, v48
	v_fma_f32 v48, -v48, v48, 1.0
	v_max_f32_e32 v48, 0, v48
	v_sqrt_f32_e32 v48, v48
	s_nop 0
	v_mul_f32_e32 v48, v49, v48
	v_mul_f32_e32 v68, v48, v68
	v_fmamk_f32 v48, v54, 0xbfb8aa3b, v30
	v_exp_f32_e32 v48, v48
	v_fmamk_f32 v49, v50, 0xbfb8aa3b, v34
	v_exp_f32_e32 v49, v49
	v_add_f32_e32 v48, 1.0, v48
	v_rcp_f32_e32 v48, v48
	v_add_f32_e32 v49, 1.0, v49
	v_rcp_f32_e32 v49, v49
	v_mul_f32_e32 v48, v48, v150
	v_exp_f32_e32 v48, v48
	s_nop 0
	v_sub_f32_e32 v53, 1.0, v48
	v_fma_f32 v48, -v48, v48, 1.0
	v_max_f32_e32 v48, 0, v48
	v_sqrt_f32_e32 v48, v48
	s_nop 0
	v_mul_f32_e32 v48, v49, v48
	v_mul_f32_e32 v54, v48, v74
	v_fmamk_f32 v48, v55, 0xbfb8aa3b, v31
	v_exp_f32_e32 v48, v48
	v_fmamk_f32 v49, v51, 0xbfb8aa3b, v35
	v_exp_f32_e32 v49, v49
	v_add_f32_e32 v48, 1.0, v48
	v_rcp_f32_e32 v48, v48
	v_add_f32_e32 v49, 1.0, v49
	v_rcp_f32_e32 v49, v49
	v_mul_f32_e32 v48, v48, v151
	v_exp_f32_e32 v48, v48
	s_nop 0
	v_sub_f32_e32 v51, 1.0, v48
	v_fma_f32 v48, -v48, v48, 1.0
	v_max_f32_e32 v48, 0, v48
	v_sqrt_f32_e32 v48, v48
	s_nop 0
	v_mul_f32_e32 v48, v49, v48
	v_mul_f32_e32 v55, v48, v66
	v_cvt_pk_bf16_f32 v48, v69, v61
	v_cvt_pk_bf16_f32 v49, v62, v63
	v_cvt_pk_bf16_f32 v50, v60, v52
	v_cvt_pk_bf16_f32 v51, v53, v51
	v_lshl_add_u64 v[52:53], s[20:21], 0, v[64:65]
	global_store_dwordx4 v[52:53], v[48:51], off sc0 sc1
	s_nop 1
	v_cvt_pk_bf16_f32 v48, v56, v57
	v_cvt_pk_bf16_f32 v49, v58, v59
	v_cvt_pk_bf16_f32 v50, v67, v68
	v_cvt_pk_bf16_f32 v51, v54, v55
	v_lshl_add_u64 v[52:53], s[34:35], 0, v[64:65]
	global_store_dwordx4 v[52:53], v[48:51], off sc0 sc1
	s_nop 1
	v_lshl_add_u64 v[48:49], v[148:149], 0, s[8:9]
	v_lshl_add_u64 v[50:51], s[30:31], 0, v[48:49]
	global_load_dwordx4 v[50:53], v[50:51], off
	s_mov_b64 s[8:9], 0x58000
	s_waitcnt vmcnt(0)
	v_lshlrev_b32_e32 v54, 16, v50
	v_and_b32_e32 v55, 0xffff0000, v50
	v_lshlrev_b32_e32 v58, 16, v53
	v_and_b32_e32 v50, 0xffff0000, v53
	v_sub_f32_e32 v53, 1.0, v36
	v_fma_f32 v36, -v36, v36, 1.0
	v_max_f32_e32 v36, 0, v36
	v_sqrt_f32_e32 v36, v36
	v_lshlrev_b32_e32 v56, 16, v51
	v_and_b32_e32 v51, 0xffff0000, v51
	v_lshlrev_b32_e32 v57, 16, v52
	v_mul_f32_e32 v24, v24, v36
	v_fmamk_f32 v36, v37, 0xbfb8aa3b, v41
	v_exp_f32_e32 v36, v36
	v_and_b32_e32 v52, 0xffff0000, v52
	v_mul_f32_e32 v24, v24, v54
	v_add_f32_e32 v36, 1.0, v36
	v_rcp_f32_e32 v36, v36
	s_nop 0
	v_mul_f32_e32 v36, v36, v190
	v_exp_f32_e32 v36, v36
	s_nop 0
	v_sub_f32_e32 v37, 1.0, v36
	v_fma_f32 v36, -v36, v36, 1.0
	v_max_f32_e32 v36, 0, v36
	v_sqrt_f32_e32 v36, v36
	s_nop 0
	v_mul_f32_e32 v25, v25, v36
	v_fmamk_f32 v36, v38, 0xbfb8aa3b, v42
	v_exp_f32_e32 v36, v36
	v_mul_f32_e32 v25, v25, v55
	v_add_f32_e32 v36, 1.0, v36
	v_rcp_f32_e32 v36, v36
	s_nop 0
	v_mul_f32_e32 v36, v36, v191
	v_exp_f32_e32 v36, v36
	s_nop 0
	v_sub_f32_e32 v38, 1.0, v36
	v_fma_f32 v36, -v36, v36, 1.0
	v_max_f32_e32 v36, 0, v36
	v_sqrt_f32_e32 v36, v36
	s_nop 0
	v_mul_f32_e32 v26, v26, v36
	v_fmamk_f32 v36, v39, 0xbfb8aa3b, v43
	v_exp_f32_e32 v36, v36
	v_mul_f32_e32 v26, v26, v56
	v_add_f32_e32 v36, 1.0, v36
	v_rcp_f32_e32 v36, v36
	s_nop 0
	v_mul_f32_e32 v36, v36, v192
	v_exp_f32_e32 v36, v36
	s_nop 0
	v_sub_f32_e32 v39, 1.0, v36
	v_fma_f32 v36, -v36, v36, 1.0
	v_max_f32_e32 v36, 0, v36
	v_sqrt_f32_e32 v36, v36
	s_nop 0
	v_mul_f32_e32 v27, v27, v36
	v_sub_f32_e32 v36, 1.0, v20
	v_fma_f32 v20, -v20, v20, 1.0
	v_max_f32_e32 v20, 0, v20
	v_sqrt_f32_e32 v20, v20
	v_mul_f32_e32 v27, v27, v51
	v_mul_f32_e32 v16, v16, v20
	v_mul_f32_e32 v51, v16, v57
	v_fmamk_f32 v16, v21, 0xbfb8aa3b, v29
	v_exp_f32_e32 v16, v16
	s_nop 0
	v_add_f32_e32 v16, 1.0, v16
	v_rcp_f32_e32 v16, v16
	s_nop 0
	v_mul_f32_e32 v16, v16, v189
	v_exp_f32_e32 v16, v16
	s_nop 0
	v_sub_f32_e32 v20, 1.0, v16
	v_fma_f32 v16, -v16, v16, 1.0
	v_max_f32_e32 v16, 0, v16
	v_sqrt_f32_e32 v16, v16
	s_nop 0
	v_mul_f32_e32 v16, v17, v16
	v_mul_f32_e32 v52, v16, v52
	v_fmamk_f32 v16, v22, 0xbfb8aa3b, v30
	v_exp_f32_e32 v16, v16
	v_fmamk_f32 v17, v18, 0xbfb8aa3b, v34
	v_exp_f32_e32 v17, v17
	v_add_f32_e32 v16, 1.0, v16
	v_rcp_f32_e32 v16, v16
	v_add_f32_e32 v17, 1.0, v17
	v_rcp_f32_e32 v17, v17
	v_mul_f32_e32 v16, v16, v150
	v_exp_f32_e32 v16, v16
	s_nop 0
	v_sub_f32_e32 v21, 1.0, v16
	v_fma_f32 v16, -v16, v16, 1.0
	v_max_f32_e32 v16, 0, v16
	v_sqrt_f32_e32 v16, v16
	s_nop 0
	v_mul_f32_e32 v16, v17, v16
	v_mul_f32_e32 v22, v16, v58
	v_fmamk_f32 v16, v23, 0xbfb8aa3b, v31
	v_exp_f32_e32 v16, v16
	v_fmamk_f32 v17, v19, 0xbfb8aa3b, v35
	v_exp_f32_e32 v17, v17
	v_add_f32_e32 v16, 1.0, v16
	v_rcp_f32_e32 v16, v16
	v_add_f32_e32 v17, 1.0, v17
	v_rcp_f32_e32 v17, v17
	v_mul_f32_e32 v16, v16, v151
	v_exp_f32_e32 v16, v16
	s_nop 0
	v_sub_f32_e32 v19, 1.0, v16
	v_fma_f32 v16, -v16, v16, 1.0
	v_max_f32_e32 v16, 0, v16
	v_sqrt_f32_e32 v16, v16
	s_nop 0
	v_mul_f32_e32 v16, v17, v16
	v_mul_f32_e32 v23, v16, v50
	v_cvt_pk_bf16_f32 v16, v53, v37
	v_cvt_pk_bf16_f32 v17, v38, v39
	v_cvt_pk_bf16_f32 v18, v36, v20
	v_cvt_pk_bf16_f32 v19, v21, v19
	v_lshl_add_u64 v[20:21], s[20:21], 0, v[48:49]
	global_store_dwordx4 v[20:21], v[16:19], off sc0 sc1
	s_nop 1
	v_cvt_pk_bf16_f32 v16, v24, v25
	v_cvt_pk_bf16_f32 v17, v26, v27
	v_cvt_pk_bf16_f32 v18, v51, v52
	v_cvt_pk_bf16_f32 v19, v22, v23
	v_lshl_add_u64 v[20:21], s[34:35], 0, v[48:49]
	global_store_dwordx4 v[20:21], v[16:19], off sc0 sc1
	s_nop 1
	v_lshl_add_u64 v[16:17], v[148:149], 0, s[8:9]
	v_lshl_add_u64 v[18:19], s[30:31], 0, v[16:17]
	global_load_dwordx4 v[18:21], v[18:19], off
	s_waitcnt vmcnt(0)
	v_lshlrev_b32_e32 v22, 16, v18
	v_and_b32_e32 v23, 0xffff0000, v18
	v_lshlrev_b32_e32 v26, 16, v21
	v_and_b32_e32 v18, 0xffff0000, v21
	v_sub_f32_e32 v21, 1.0, v12
	v_fma_f32 v12, -v12, v12, 1.0
	v_max_f32_e32 v12, 0, v12
	v_sqrt_f32_e32 v12, v12
	v_lshlrev_b32_e32 v24, 16, v19
	v_and_b32_e32 v19, 0xffff0000, v19
	v_lshlrev_b32_e32 v25, 16, v20
	v_mul_f32_e32 v8, v8, v12
	v_fmamk_f32 v12, v13, 0xbfb8aa3b, v41
	v_exp_f32_e32 v12, v12
	v_and_b32_e32 v20, 0xffff0000, v20
	v_mul_f32_e32 v8, v8, v22
	v_add_f32_e32 v12, 1.0, v12
	v_rcp_f32_e32 v12, v12
	s_nop 0
	v_mul_f32_e32 v12, v12, v190
	v_exp_f32_e32 v12, v12
	s_nop 0
	v_sub_f32_e32 v13, 1.0, v12
	v_fma_f32 v12, -v12, v12, 1.0
	v_max_f32_e32 v12, 0, v12
	v_sqrt_f32_e32 v12, v12
	s_nop 0
	v_mul_f32_e32 v9, v9, v12
	v_fmamk_f32 v12, v14, 0xbfb8aa3b, v42
	v_exp_f32_e32 v12, v12
	v_mul_f32_e32 v9, v9, v23
	v_add_f32_e32 v12, 1.0, v12
	v_rcp_f32_e32 v12, v12
	s_nop 0
	v_mul_f32_e32 v12, v12, v191
	v_exp_f32_e32 v12, v12
	s_nop 0
	v_sub_f32_e32 v14, 1.0, v12
	v_fma_f32 v12, -v12, v12, 1.0
	v_max_f32_e32 v12, 0, v12
	v_sqrt_f32_e32 v12, v12
	s_nop 0
	v_mul_f32_e32 v10, v10, v12
	v_fmamk_f32 v12, v15, 0xbfb8aa3b, v43
	v_exp_f32_e32 v12, v12
	v_mul_f32_e32 v10, v10, v24
	v_add_f32_e32 v12, 1.0, v12
	v_rcp_f32_e32 v12, v12
	s_nop 0
	v_mul_f32_e32 v12, v12, v192
	v_exp_f32_e32 v12, v12
	s_nop 0
	v_sub_f32_e32 v15, 1.0, v12
	v_fma_f32 v12, -v12, v12, 1.0
	v_max_f32_e32 v12, 0, v12
	v_sqrt_f32_e32 v12, v12
	s_nop 0
	v_mul_f32_e32 v11, v11, v12
	v_sub_f32_e32 v12, 1.0, v4
	v_fma_f32 v4, -v4, v4, 1.0
	v_max_f32_e32 v4, 0, v4
	v_sqrt_f32_e32 v4, v4
	v_mul_f32_e32 v11, v11, v19
	v_mul_f32_e32 v0, v0, v4
	v_mul_f32_e32 v19, v0, v25
	v_fmamk_f32 v0, v5, 0xbfb8aa3b, v29
	v_exp_f32_e32 v0, v0
	s_nop 0
	v_add_f32_e32 v0, 1.0, v0
	v_rcp_f32_e32 v0, v0
	s_nop 0
	v_mul_f32_e32 v0, v0, v189
	v_exp_f32_e32 v0, v0
	s_nop 0
	v_sub_f32_e32 v4, 1.0, v0
	v_fma_f32 v0, -v0, v0, 1.0
	v_max_f32_e32 v0, 0, v0
	v_sqrt_f32_e32 v0, v0
	s_nop 0
	v_mul_f32_e32 v0, v1, v0
	v_mul_f32_e32 v20, v0, v20
	v_fmamk_f32 v0, v6, 0xbfb8aa3b, v30
	v_exp_f32_e32 v0, v0
	v_fmamk_f32 v1, v2, 0xbfb8aa3b, v34
	v_exp_f32_e32 v1, v1
	v_add_f32_e32 v0, 1.0, v0
	v_rcp_f32_e32 v0, v0
	v_add_f32_e32 v1, 1.0, v1
	v_rcp_f32_e32 v1, v1
	v_mul_f32_e32 v0, v0, v150
	v_exp_f32_e32 v0, v0
	s_nop 0
	v_sub_f32_e32 v5, 1.0, v0
	v_fma_f32 v0, -v0, v0, 1.0
	v_max_f32_e32 v0, 0, v0
	v_sqrt_f32_e32 v0, v0
	s_nop 0
	v_mul_f32_e32 v0, v1, v0
	v_mul_f32_e32 v6, v0, v26
	v_fmamk_f32 v0, v7, 0xbfb8aa3b, v31
	v_exp_f32_e32 v0, v0
	v_fmamk_f32 v1, v3, 0xbfb8aa3b, v35
	v_exp_f32_e32 v1, v1
	v_add_f32_e32 v0, 1.0, v0
	v_rcp_f32_e32 v0, v0
	v_add_f32_e32 v1, 1.0, v1
	v_rcp_f32_e32 v1, v1
	v_mul_f32_e32 v0, v0, v151
	v_exp_f32_e32 v0, v0
	s_nop 0
	v_sub_f32_e32 v3, 1.0, v0
	v_fma_f32 v0, -v0, v0, 1.0
	v_max_f32_e32 v0, 0, v0
	v_sqrt_f32_e32 v0, v0
	s_nop 0
	v_mul_f32_e32 v0, v1, v0
	v_mul_f32_e32 v7, v0, v18
	v_cvt_pk_bf16_f32 v0, v21, v13
	v_cvt_pk_bf16_f32 v1, v14, v15
	v_cvt_pk_bf16_f32 v2, v12, v4
	v_cvt_pk_bf16_f32 v3, v5, v3
	v_lshl_add_u64 v[4:5], s[20:21], 0, v[16:17]
	global_store_dwordx4 v[4:5], v[0:3], off sc0 sc1
	s_nop 1
	v_cvt_pk_bf16_f32 v0, v8, v9
	v_cvt_pk_bf16_f32 v1, v10, v11
	v_cvt_pk_bf16_f32 v2, v19, v20
	v_cvt_pk_bf16_f32 v3, v6, v7
	v_lshl_add_u64 v[4:5], s[34:35], 0, v[16:17]
	global_store_dwordx4 v[4:5], v[0:3], off sc0 sc1
	s_nop 1
	s_nop 0
	s_mov_b64 s[36:37], exec
	v_readlane_b32 s8, v254, 0
	v_readlane_b32 s9, v254, 1
	s_and_b64 s[8:9], s[36:37], s[8:9]
	s_mov_b64 exec, s[8:9]
	s_cbranch_execz .LBB0_464
	s_mov_b64 s[38:39], exec
	v_mbcnt_lo_u32_b32 v0, s38, 0
	v_mbcnt_hi_u32_b32 v0, s39, v0
	v_cmp_eq_u32_e32 vcc, 0, v0
	s_and_b64 s[8:9], exec, vcc
	s_mov_b64 exec, s[8:9]
	s_cbranch_execz .LBB0_464
	s_lshl_b32 s0, s0, 6
	s_ashr_i32 s1, s0, 31
	s_lshl_b64 s[0:1], s[0:1], 2
	v_readlane_b32 s4, v254, 51
	v_readlane_b32 s5, v254, 52
	s_add_u32 s0, s4, s0
	s_addc_u32 s1, s5, s1
	s_bcnt1_i32_b64 s8, s[38:39]
	v_mov_b32_e32 v0, s8
	s_sub_u32 s98, s0, 1
	s_subb_u32 s99, s1, 0
